# S5 first pass software-pipelined: projection of chunk i+1 (batched MFMAs) issued before the scan of chunk i
# baseline (speedup 1.0000x reference)
.LBB0_991:
	s_or_b64 exec, exec, s[14:15]
	s_waitcnt vmcnt(25)
	v_cvt_pk_bf16_f32 v2, v114, v115
	v_cvt_pk_bf16_f32 v3, v104, v105
	s_waitcnt vmcnt(22)
	v_cvt_pk_bf16_f32 v88, v88, v89
	v_cvt_pk_bf16_f32 v89, v90, v91
	s_waitcnt vmcnt(19)
	v_cvt_pk_bf16_f32 v90, v92, v93
	s_waitcnt vmcnt(12)
	v_cvt_pk_bf16_f32 v92, v4, v5
	v_cndmask_b32_e64 v5, 0, v2, s[4:5]
	v_add_u32_e32 v2, v117, v137
	v_cvt_pk_bf16_f32 v93, v6, v7
	v_cndmask_b32_e64 v6, 0, v3, s[4:5]
	v_ashrrev_i32_e32 v3, 31, v2
	v_lshlrev_b64 v[2:3], 11, v[2:3]
	v_cvt_pk_bf16_f32 v32, v32, v33
	v_cvt_pk_bf16_f32 v33, v34, v35
	v_cvt_pk_bf16_f32 v34, v84, v85
	v_lshl_or_b32 v2, v175, 5, v2
	v_cvt_pk_bf16_f32 v1, v112, v113
	v_cvt_pk_bf16_f32 v104, v106, v107
	v_cvt_pk_bf16_f32 v105, v108, v109
	v_cvt_pk_bf16_f32 v106, v110, v111
	v_cvt_pk_bf16_f32 v96, v96, v97
	v_cvt_pk_bf16_f32 v97, v98, v99
	v_cvt_pk_bf16_f32 v98, v100, v101
	v_cvt_pk_bf16_f32 v99, v102, v103
	v_cvt_pk_bf16_f32 v91, v94, v95
	v_cvt_pk_bf16_f32 v35, v86, v87
	v_cvt_pk_bf16_f32 v24, v24, v25
	v_cvt_pk_bf16_f32 v25, v26, v27
	v_cvt_pk_bf16_f32 v28, v28, v29
	v_cvt_pk_bf16_f32 v29, v30, v31
	v_cvt_pk_bf16_f32 v26, v16, v17
	v_cvt_pk_bf16_f32 v27, v18, v19
	v_cvt_pk_bf16_f32 v84, v20, v21
	v_cvt_pk_bf16_f32 v85, v22, v23
	v_cvt_pk_bf16_f32 v30, v8, v9
	v_cvt_pk_bf16_f32 v31, v10, v11
	s_waitcnt vmcnt(11)
	v_cvt_pk_bf16_f32 v86, v12, v13
	v_cvt_pk_bf16_f32 v87, v14, v15
	v_cndmask_b32_e64 v15, 0, v89, s[4:5]
	v_cndmask_b32_e64 v14, 0, v88, s[4:5]
	v_cndmask_b32_e64 v20, 0, v34, s[4:5]
	v_cndmask_b32_e64 v34, 0, v92, s[4:5]
	v_lshl_add_u64 v[88:89], v[130:131], 0, v[2:3]
	v_mov_b32_e32 v92, 0
	v_cndmask_b32_e64 v7, 0, v104, s[4:5]
	v_cndmask_b32_e64 v4, 0, v1, s[4:5]
	v_cndmask_b32_e64 v11, 0, v97, s[4:5]
	v_cndmask_b32_e64 v10, 0, v96, s[4:5]
	v_cndmask_b32_e64 v9, 0, v106, s[4:5]
	v_cndmask_b32_e64 v8, 0, v105, s[4:5]
	v_cndmask_b32_e64 v13, 0, v99, s[4:5]
	v_cndmask_b32_e64 v12, 0, v98, s[4:5]
	v_cndmask_b32_e64 v19, 0, v33, s[4:5]
	v_cndmask_b32_e64 v18, 0, v32, s[4:5]
	v_cndmask_b32_e64 v17, 0, v91, s[4:5]
	v_cndmask_b32_e64 v16, 0, v90, s[4:5]
	v_cndmask_b32_e64 v23, 0, v25, s[4:5]
	v_cndmask_b32_e64 v22, 0, v24, s[4:5]
	v_cndmask_b32_e64 v21, 0, v35, s[4:5]
	v_cndmask_b32_e64 v27, 0, v27, s[4:5]
	v_cndmask_b32_e64 v26, 0, v26, s[4:5]
	v_cndmask_b32_e64 v25, 0, v29, s[4:5]
	v_cndmask_b32_e64 v24, 0, v28, s[4:5]
	v_cndmask_b32_e64 v31, 0, v31, s[4:5]
	v_cndmask_b32_e64 v30, 0, v30, s[4:5]
	v_cndmask_b32_e64 v29, 0, v85, s[4:5]
	v_cndmask_b32_e64 v28, 0, v84, s[4:5]
	v_cndmask_b32_e64 v35, 0, v93, s[4:5]
	v_cndmask_b32_e64 v33, 0, v87, s[4:5]
	v_cndmask_b32_e64 v32, 0, v86, s[4:5]
	s_waitcnt vmcnt(2)
	v_mov_b32_e32 v139, v138
	s_waitcnt vmcnt(1)
	v_mov_b32_e32 v141, v140
	s_mov_b32 s16, -16
	v_mov_b64_e32 v[90:91], v[88:89]
	v_mov_b32_e32 v93, v92
	s_waitcnt vmcnt(0)
	v_add_u32_e32 v94, 0x400, v158
	v_add_u32_e32 v95, 0x400, v159
	v_add_u32_e32 v96, 0x800, v173
	v_add_u32_e32 v97, 0x1000, v173
	v_add_u32_e32 v98, 0x1800, v173
	v_add_u32_e32 v250, 0x400, v157
	v_mfma_f32_16x16x32_bf16 v[212:215], v[80:83], v[4:7], 0
	v_mfma_f32_16x16x32_bf16 v[216:219], v[80:83], v[8:11], 0
	v_mfma_f32_16x16x32_bf16 v[220:223], v[80:83], v[12:15], 0
	v_mfma_f32_16x16x32_bf16 v[224:227], v[80:83], v[16:19], 0
	v_mfma_f32_16x16x32_bf16 v[232:235], v[80:83], v[20:23], 0
	v_mfma_f32_16x16x32_bf16 v[236:239], v[80:83], v[24:27], 0
	v_mfma_f32_16x16x32_bf16 v[240:243], v[80:83], v[28:31], 0
	v_mfma_f32_16x16x32_bf16 v[244:247], v[80:83], v[32:35], 0
	s_nop 7
	ds_write2_b32 v157, v212, v213 offset0:0 offset1:132
	ds_write2_b32 v250, v214, v215 offset0:8 offset1:140
	ds_write2_b32 v157, v216, v217 offset0:16 offset1:148
	ds_write2_b32 v250, v218, v219 offset0:24 offset1:156
	ds_write2_b32 v157, v220, v221 offset0:32 offset1:164
	ds_write2_b32 v250, v222, v223 offset0:40 offset1:172
	ds_write2_b32 v157, v224, v225 offset0:48 offset1:180
	ds_write2_b32 v250, v226, v227 offset0:56 offset1:188
	s_waitcnt lgkmcnt(7)
	ds_write2_b32 v157, v232, v233 offset0:64 offset1:196
	ds_write2_b32 v250, v234, v235 offset0:72 offset1:204
	ds_write2_b32 v157, v236, v237 offset0:80 offset1:212
	ds_write2_b32 v250, v238, v239 offset0:88 offset1:220
	ds_write2_b32 v157, v240, v241 offset0:96 offset1:228
	ds_write2_b32 v250, v242, v243 offset0:104 offset1:236
	ds_write2_b32 v157, v244, v245 offset0:112 offset1:244
	ds_write2_b32 v250, v246, v247 offset0:120 offset1:252
	s_branch .LBB0_993
.LBB0_992:
	s_or_b64 exec, exec, s[14:15]
	ds_read2_b64 v[80:83], v173 offset1:66
	ds_read2_b64 v[100:103], v173 offset0:132 offset1:198
	ds_read2_b64 v[104:107], v96 offset0:8 offset1:74
	ds_read2_b64 v[108:111], v96 offset0:140 offset1:206
	ds_read2_b64 v[112:115], v97 offset0:16 offset1:82
	ds_read2_b64 v[176:179], v97 offset0:148 offset1:214
	ds_read2_b64 v[180:183], v98 offset0:24 offset1:90
	ds_read2_b64 v[184:187], v98 offset0:156 offset1:222
	v_mfma_f32_16x16x32_bf16 v[212:215], v[68:71], v[4:7], 0
	v_mfma_f32_16x16x32_bf16 v[216:219], v[68:71], v[8:11], 0
	v_mfma_f32_16x16x32_bf16 v[220:223], v[68:71], v[12:15], 0
	v_mfma_f32_16x16x32_bf16 v[224:227], v[68:71], v[16:19], 0
	v_mfma_f32_16x16x32_bf16 v[232:235], v[68:71], v[20:23], 0
	v_mfma_f32_16x16x32_bf16 v[236:239], v[68:71], v[24:27], 0
	v_mfma_f32_16x16x32_bf16 v[240:243], v[68:71], v[28:31], 0
	v_mfma_f32_16x16x32_bf16 v[244:247], v[68:71], v[32:35], 0
	v_lshl_add_u64 v[90:91], v[90:91], 0, s[12:13]
	s_cmpk_lt_u32 s16, 0x1f0
	s_waitcnt lgkmcnt(0)
	s_nop 1
	ds_write2_b32 v157, v212, v213 offset0:0 offset1:132
	ds_write2_b32 v250, v214, v215 offset0:8 offset1:140
	ds_write2_b32 v157, v216, v217 offset0:16 offset1:148
	ds_write2_b32 v250, v218, v219 offset0:24 offset1:156
	ds_write2_b32 v157, v220, v221 offset0:32 offset1:164
	ds_write2_b32 v250, v222, v223 offset0:40 offset1:172
	ds_write2_b32 v157, v224, v225 offset0:48 offset1:180
	ds_write2_b32 v250, v226, v227 offset0:56 offset1:188
	s_waitcnt lgkmcnt(7)
	ds_write2_b32 v157, v232, v233 offset0:64 offset1:196
	ds_write2_b32 v250, v234, v235 offset0:72 offset1:204
	ds_write2_b32 v157, v236, v237 offset0:80 offset1:212
	ds_write2_b32 v250, v238, v239 offset0:88 offset1:220
	ds_write2_b32 v157, v240, v241 offset0:96 offset1:228
	ds_write2_b32 v250, v242, v243 offset0:104 offset1:236
	ds_write2_b32 v157, v244, v245 offset0:112 offset1:244
	ds_write2_b32 v250, v246, v247 offset0:120 offset1:252
	v_fma_f32 v248, v138, v92, v80
	v_fma_f32 v249, v138, v93, v81
	v_fma_f32 v2, -v140, v93, v248
	v_fma_f32 v3, v140, v92, v249
	v_fma_f32 v248, v138, v2, v82
	v_fma_f32 v249, v138, v3, v83
	v_fma_f32 v92, -v140, v3, v248
	v_fma_f32 v93, v140, v2, v249
	v_fma_f32 v248, v138, v92, v100
	v_fma_f32 v249, v138, v93, v101
	v_fma_f32 v2, -v140, v93, v248
	v_fma_f32 v3, v140, v92, v249
	v_fma_f32 v248, v138, v2, v102
	v_fma_f32 v249, v138, v3, v103
	v_fma_f32 v92, -v140, v3, v248
	v_fma_f32 v93, v140, v2, v249
	v_fma_f32 v248, v138, v92, v104
	v_fma_f32 v249, v138, v93, v105
	v_fma_f32 v2, -v140, v93, v248
	v_fma_f32 v3, v140, v92, v249
	v_fma_f32 v248, v138, v2, v106
	v_fma_f32 v249, v138, v3, v107
	v_fma_f32 v92, -v140, v3, v248
	v_fma_f32 v93, v140, v2, v249
	v_fma_f32 v248, v138, v92, v108
	v_fma_f32 v249, v138, v93, v109
	v_fma_f32 v2, -v140, v93, v248
	v_fma_f32 v3, v140, v92, v249
	v_fma_f32 v248, v138, v2, v110
	v_fma_f32 v249, v138, v3, v111
	v_fma_f32 v92, -v140, v3, v248
	v_fma_f32 v93, v140, v2, v249
	v_fma_f32 v248, v138, v92, v112
	v_fma_f32 v249, v138, v93, v113
	v_fma_f32 v2, -v140, v93, v248
	v_fma_f32 v3, v140, v92, v249
	v_fma_f32 v248, v138, v2, v114
	v_fma_f32 v249, v138, v3, v115
	v_fma_f32 v92, -v140, v3, v248
	v_fma_f32 v93, v140, v2, v249
	v_fma_f32 v248, v138, v92, v176
	v_fma_f32 v249, v138, v93, v177
	v_fma_f32 v2, -v140, v93, v248
	v_fma_f32 v3, v140, v92, v249
	v_fma_f32 v248, v138, v2, v178
	v_fma_f32 v249, v138, v3, v179
	v_fma_f32 v92, -v140, v3, v248
	v_fma_f32 v93, v140, v2, v249
	v_fma_f32 v248, v138, v92, v180
	v_fma_f32 v249, v138, v93, v181
	v_fma_f32 v2, -v140, v93, v248
	v_fma_f32 v3, v140, v92, v249
	v_fma_f32 v248, v138, v2, v182
	v_fma_f32 v249, v138, v3, v183
	v_fma_f32 v92, -v140, v3, v248
	v_fma_f32 v93, v140, v2, v249
	v_fma_f32 v248, v138, v92, v184
	v_fma_f32 v249, v138, v93, v185
	v_fma_f32 v2, -v140, v93, v248
	v_fma_f32 v3, v140, v92, v249
	v_fma_f32 v248, v138, v2, v186
	v_fma_f32 v249, v138, v3, v187
	v_fma_f32 v92, -v140, v3, v248
	v_fma_f32 v93, v140, v2, v249
	v_mov_b64_e32 v[82:83], v[70:71]
	v_mov_b64_e32 v[80:81], v[68:69]
	v_mov_b64_e32 v[68:69], v[72:73]
	v_mov_b64_e32 v[70:71], v[74:75]
	v_mov_b64_e32 v[72:73], v[76:77]
	v_mov_b64_e32 v[74:75], v[78:79]
	s_waitcnt vmcnt(0)
	v_mov_b64_e32 v[76:77], v[84:85]
	v_mov_b64_e32 v[78:79], v[86:87]
	s_cbranch_scc0 .LBB0_995
